# step barrier: release polling without s_sleep (s_nop 7 between polls)
# speedup vs baseline: 1.0038x; 1.0034x over previous
.LBB0_1192:
	s_and_b32 s22, s26, 0xff
	s_mov_b64 s[20:21], -1
	s_cmp_lg_u32 s22, 0
	s_mov_b64 s[24:25], -1
	s_nop 7
	s_cbranch_scc1 .LBB0_1195
	global_load_dword v0, v193, s[12:13] sc1
	s_waitcnt vmcnt(0)
	v_cmp_eq_u32_e32 vcc, 0, v0
	s_cbranch_vccnz .LBB0_1197
	s_mov_b64 s[24:25], 0
	s_mov_b64 s[22:23], -1

.LBB0_1209:
	s_and_b32 s20, s24, 0xff
	s_mov_b64 s[18:19], -1
	s_cmp_lg_u32 s20, 0
	s_mov_b64 s[22:23], -1
	s_nop 7
	s_cbranch_scc1 .LBB0_1212
	global_load_dword v0, v193, s[12:13] sc1
	s_waitcnt vmcnt(0)
	v_cmp_eq_u32_e32 vcc, 0, v0
	s_cbranch_vccnz .LBB0_1214
	s_mov_b64 s[22:23], 0
	s_mov_b64 s[20:21], -1
